# P3 epilogue: 8 cols per lane, dwordx4 bf16 stores (8 per half instead of 16 dwordx2), x loads batched
# baseline (speedup 1.0000x reference)
; DI unsigned pack2(float a, float b) { const f32x2 v = {a, b}; const bf16x2_t r = __builtin_convertvector(v, bf16x2_t); return __builtin_bit_cast(unsigned, r); }
; DI void outproj_epilogue(const Params& p, const char* smem, const int m0, const int n0) {
;   u16* rbuf = (u16*)(p.ws + WS_PU);
;   const float* ct = (const float*)smem;
; #pragma unroll 4
;   for (int i = 0; i < 16; ++i) {
;     const int c = threadIdx.x + NT * i, row = c >> 5, ch = c & 31;
;     const float4 y = *(const float4*)(ct + row * CT_PITCH + 4 * ch);
;     const size_t o = (size_t)(m0 + row) * 1024 + n0 + 4 * ch;
;     const float4 xv = *(const float4*)(p.x + o), bv = *(const float4*)(p.b_out + n0 + 4 * ch);
;     uint2 r; r.x = pack2(ALPHA * xv.x + y.x + bv.x, ALPHA * xv.y + y.y + bv.y); r.y = pack2(ALPHA * xv.z + y.z + bv.z, ALPHA * xv.w + y.w + bv.w);
;     *(uint2*)(rbuf + o) = r;
;   }
.LBB0_294:
	s_ashr_i32 s27, s26, 31
	v_mov_b32_e32 v141, s27
	v_or_b32_e32 v140, s26, v130
	v_lshl_add_u64 v[138:139], s[26:27], 2, v[136:137]
	v_add_u32_e32 v162, s0, v149
	v_add_u32_e32 v163, s0, v151
	v_add_u32_e32 v164, s0, v153
	s_mov_b32 s0, 0
	v_mov_b32_e32 v165, v154
	v_mov_b32_e32 v166, v152
	v_mov_b32_e32 v167, v150
	v_lshrrev_b32_e32 v187, 4, v0
	v_sub_u32_e32 v184, v164, v153
	v_add_u32_e32 v187, v184, v187
	v_and_b32_e32 v184, 15, v0
	v_lshl_or_b32 v184, v184, 3, s26
	v_lshlrev_b32_e32 v164, 2, v184
	v_lshl_add_u32 v184, v187, 10, v184
	v_lshlrev_b32_e32 v185, 1, v184
	v_lshlrev_b32_e32 v184, 2, v184
	v_readlane_b32 s100, v239, 0
	v_readlane_b32 s101, v239, 1
	v_lshrrev_b32_e32 v187, 4, v0
	v_and_b32_e32 v186, 15, v0
	v_lshlrev_b32_e32 v186, 5, v186
	v_mul_u32_u24_e32 v187, 0x210, v187
	v_add_u32_e32 v186, v187, v186
	s_nop 1
	global_load_dwordx4 v[168:171], v164, s[100:101] offset:0
	global_load_dwordx4 v[172:175], v164, s[100:101] offset:16
	s_mov_b64 s[98:99], s[52:53]
	global_load_dwordx4 v[188:191], v184, s[98:99] offset:0
	global_load_dwordx4 v[192:195], v184, s[98:99] offset:16
	s_add_u32 s98, s98, 0x20000
	s_addc_u32 s99, s99, 0
	global_load_dwordx4 v[196:199], v184, s[98:99] offset:0
	global_load_dwordx4 v[202:205], v184, s[98:99] offset:16
	s_add_u32 s98, s98, 0x20000
	s_addc_u32 s99, s99, 0
	global_load_dwordx4 v[206:209], v184, s[98:99] offset:0
	global_load_dwordx4 v[210:213], v184, s[98:99] offset:16
	s_add_u32 s98, s98, 0x20000
	s_addc_u32 s99, s99, 0
	global_load_dwordx4 v[214:217], v184, s[98:99] offset:0
	global_load_dwordx4 v[218:221], v184, s[98:99] offset:16
	s_add_u32 s98, s98, 0x20000
	s_addc_u32 s99, s99, 0
	global_load_dwordx4 v[222:225], v184, s[98:99] offset:0
	global_load_dwordx4 v[226:229], v184, s[98:99] offset:16
	s_add_u32 s98, s98, 0x20000
	s_addc_u32 s99, s99, 0
	global_load_dwordx4 v[230:233], v184, s[98:99] offset:0
	global_load_dwordx4 v[234:237], v184, s[98:99] offset:16
	s_add_u32 s98, s98, 0x20000
	s_addc_u32 s99, s99, 0
	global_load_dwordx4 v[240:243], v184, s[98:99] offset:0
	global_load_dwordx4 v[244:247], v184, s[98:99] offset:16
	s_add_u32 s98, s98, 0x20000
	s_addc_u32 s99, s99, 0
	global_load_dwordx4 v[248:251], v184, s[98:99] offset:0
	global_load_dwordx4 v[252:255], v184, s[98:99] offset:16
	s_waitcnt lgkmcnt(0)
	s_barrier
	s_mov_b64 s[98:99], s[14:15]
	ds_read_b128 v[176:179], v186
	ds_read_b128 v[180:183], v186 offset:16
	s_waitcnt vmcnt(14) lgkmcnt(0)
	v_pk_fma_f32 v[188:189], v[188:189], s[24:25], v[176:177] op_sel_hi:[1,0,1]
	v_pk_fma_f32 v[190:191], v[190:191], s[24:25], v[178:179] op_sel_hi:[1,0,1]
	v_pk_fma_f32 v[192:193], v[192:193], s[24:25], v[180:181] op_sel_hi:[1,0,1]
	v_pk_fma_f32 v[194:195], v[194:195], s[24:25], v[182:183] op_sel_hi:[1,0,1]
	v_add_u32_e32 v186, 0x4200, v186
	ds_read_b128 v[176:179], v186
	ds_read_b128 v[180:183], v186 offset:16
	v_pk_add_f32 v[188:189], v[188:189], v[168:169]
	v_pk_add_f32 v[190:191], v[190:191], v[170:171]
	v_pk_add_f32 v[192:193], v[192:193], v[172:173]
	v_pk_add_f32 v[194:195], v[194:195], v[174:175]
	v_cvt_pk_bf16_f32 v188, v188, v189
	v_cvt_pk_bf16_f32 v189, v190, v191
	v_cvt_pk_bf16_f32 v190, v192, v193
	v_cvt_pk_bf16_f32 v191, v194, v195
	global_store_dwordx4 v185, v[188:191], s[98:99] offset:0
	s_add_u32 s98, s98, 0x10000
	s_addc_u32 s99, s99, 0
	s_waitcnt vmcnt(13) lgkmcnt(0)
	v_pk_fma_f32 v[196:197], v[196:197], s[24:25], v[176:177] op_sel_hi:[1,0,1]
	v_pk_fma_f32 v[198:199], v[198:199], s[24:25], v[178:179] op_sel_hi:[1,0,1]
	v_pk_fma_f32 v[202:203], v[202:203], s[24:25], v[180:181] op_sel_hi:[1,0,1]
	v_pk_fma_f32 v[204:205], v[204:205], s[24:25], v[182:183] op_sel_hi:[1,0,1]
	v_add_u32_e32 v186, 0x4200, v186
	ds_read_b128 v[176:179], v186
	ds_read_b128 v[180:183], v186 offset:16
	v_pk_add_f32 v[196:197], v[196:197], v[168:169]
	v_pk_add_f32 v[198:199], v[198:199], v[170:171]
	v_pk_add_f32 v[202:203], v[202:203], v[172:173]
	v_pk_add_f32 v[204:205], v[204:205], v[174:175]
	v_cvt_pk_bf16_f32 v196, v196, v197
	v_cvt_pk_bf16_f32 v197, v198, v199
	v_cvt_pk_bf16_f32 v198, v202, v203
	v_cvt_pk_bf16_f32 v199, v204, v205
	global_store_dwordx4 v185, v[196:199], s[98:99] offset:0
	s_add_u32 s98, s98, 0x10000
	s_addc_u32 s99, s99, 0
	s_waitcnt vmcnt(12) lgkmcnt(0)
	v_pk_fma_f32 v[206:207], v[206:207], s[24:25], v[176:177] op_sel_hi:[1,0,1]
	v_pk_fma_f32 v[208:209], v[208:209], s[24:25], v[178:179] op_sel_hi:[1,0,1]
	v_pk_fma_f32 v[210:211], v[210:211], s[24:25], v[180:181] op_sel_hi:[1,0,1]
	v_pk_fma_f32 v[212:213], v[212:213], s[24:25], v[182:183] op_sel_hi:[1,0,1]
	v_add_u32_e32 v186, 0x4200, v186
	ds_read_b128 v[176:179], v186
	ds_read_b128 v[180:183], v186 offset:16
	v_pk_add_f32 v[206:207], v[206:207], v[168:169]
	v_pk_add_f32 v[208:209], v[208:209], v[170:171]
	v_pk_add_f32 v[210:211], v[210:211], v[172:173]
	v_pk_add_f32 v[212:213], v[212:213], v[174:175]
	v_cvt_pk_bf16_f32 v206, v206, v207
	v_cvt_pk_bf16_f32 v207, v208, v209
	v_cvt_pk_bf16_f32 v208, v210, v211
	v_cvt_pk_bf16_f32 v209, v212, v213
	global_store_dwordx4 v185, v[206:209], s[98:99] offset:0
	s_add_u32 s98, s98, 0x10000
	s_addc_u32 s99, s99, 0
	s_waitcnt vmcnt(11) lgkmcnt(0)
	v_pk_fma_f32 v[214:215], v[214:215], s[24:25], v[176:177] op_sel_hi:[1,0,1]
	v_pk_fma_f32 v[216:217], v[216:217], s[24:25], v[178:179] op_sel_hi:[1,0,1]
	v_pk_fma_f32 v[218:219], v[218:219], s[24:25], v[180:181] op_sel_hi:[1,0,1]
	v_pk_fma_f32 v[220:221], v[220:221], s[24:25], v[182:183] op_sel_hi:[1,0,1]
	v_add_u32_e32 v186, 0x4200, v186
	ds_read_b128 v[176:179], v186
	ds_read_b128 v[180:183], v186 offset:16
	v_pk_add_f32 v[214:215], v[214:215], v[168:169]
	v_pk_add_f32 v[216:217], v[216:217], v[170:171]
	v_pk_add_f32 v[218:219], v[218:219], v[172:173]
	v_pk_add_f32 v[220:221], v[220:221], v[174:175]
	v_cvt_pk_bf16_f32 v214, v214, v215
	v_cvt_pk_bf16_f32 v215, v216, v217
	v_cvt_pk_bf16_f32 v216, v218, v219
	v_cvt_pk_bf16_f32 v217, v220, v221
	global_store_dwordx4 v185, v[214:217], s[98:99] offset:0
	s_add_u32 s98, s98, 0x10000
	s_addc_u32 s99, s99, 0
	s_waitcnt vmcnt(10) lgkmcnt(0)
; DI unsigned pack2(float a, float b) { const f32x2 v = {a, b}; const bf16x2_t r = __builtin_convertvector(v, bf16x2_t); return __builtin_bit_cast(unsigned, r); }
; template <int HF>
; DI void stage_acc_big(const f32x4 (&acc)[8][4], char* smem, const int g, const int r16) {
;   const int w = __builtin_amdgcn_readfirstlane(threadIdx.x >> 6), wm = w & 1, wn = w >> 1;
;   if ((wn >> 1) != HF) return;
;   float* ct = (float*)smem;
; #pragma unroll
;   for (int mi = 0; mi < 8; ++mi)
; #pragma unroll
;     for (int ni = 0; ni < 4; ++ni)
; #pragma unroll
;       for (int j = 0; j < 4; ++j) ct[(128 * wm + 16 * mi + 4 * g + j) * CT_PITCH + 64 * (wn & 1) + 16 * ni + r16] = acc[mi][ni][j];
; }
; DI void outproj_epilogue(const Params& p, const char* smem, const int m0, const int n0) {
;     ...
; #pragma unroll 4
;   for (int i = 0; i < 16; ++i) {
;     const int c = threadIdx.x + NT * i, row = c >> 5, ch = c & 31;
;     const float4 y = *(const float4*)(ct + row * CT_PITCH + 4 * ch);
;     const size_t o = (size_t)(m0 + row) * 1024 + n0 + 4 * ch;
;     const float4 xv = *(const float4*)(p.x + o), bv = *(const float4*)(p.b_out + n0 + 4 * ch);
;     uint2 r; r.x = pack2(ALPHA * xv.x + y.x + bv.x, ALPHA * xv.y + y.y + bv.y); r.y = pack2(ALPHA * xv.z + y.z + bv.z, ALPHA * xv.w + y.w + bv.w);
;     *(uint2*)(rbuf + o) = r;
;   }
	v_pk_fma_f32 v[222:223], v[222:223], s[24:25], v[176:177] op_sel_hi:[1,0,1]
	v_pk_fma_f32 v[224:225], v[224:225], s[24:25], v[178:179] op_sel_hi:[1,0,1]
	v_pk_fma_f32 v[226:227], v[226:227], s[24:25], v[180:181] op_sel_hi:[1,0,1]
	v_pk_fma_f32 v[228:229], v[228:229], s[24:25], v[182:183] op_sel_hi:[1,0,1]
	v_add_u32_e32 v186, 0x4200, v186
	ds_read_b128 v[176:179], v186
	ds_read_b128 v[180:183], v186 offset:16
	v_pk_add_f32 v[222:223], v[222:223], v[168:169]
	v_pk_add_f32 v[224:225], v[224:225], v[170:171]
	v_pk_add_f32 v[226:227], v[226:227], v[172:173]
	v_pk_add_f32 v[228:229], v[228:229], v[174:175]
	v_cvt_pk_bf16_f32 v222, v222, v223
	v_cvt_pk_bf16_f32 v223, v224, v225
	v_cvt_pk_bf16_f32 v224, v226, v227
	v_cvt_pk_bf16_f32 v225, v228, v229
	global_store_dwordx4 v185, v[222:225], s[98:99] offset:0
	s_add_u32 s98, s98, 0x10000
	s_addc_u32 s99, s99, 0
	s_waitcnt vmcnt(9) lgkmcnt(0)
	v_pk_fma_f32 v[230:231], v[230:231], s[24:25], v[176:177] op_sel_hi:[1,0,1]
	v_pk_fma_f32 v[232:233], v[232:233], s[24:25], v[178:179] op_sel_hi:[1,0,1]
	v_pk_fma_f32 v[234:235], v[234:235], s[24:25], v[180:181] op_sel_hi:[1,0,1]
	v_pk_fma_f32 v[236:237], v[236:237], s[24:25], v[182:183] op_sel_hi:[1,0,1]
	v_add_u32_e32 v186, 0x4200, v186
	ds_read_b128 v[176:179], v186
	ds_read_b128 v[180:183], v186 offset:16
	v_pk_add_f32 v[230:231], v[230:231], v[168:169]
	v_pk_add_f32 v[232:233], v[232:233], v[170:171]
	v_pk_add_f32 v[234:235], v[234:235], v[172:173]
	v_pk_add_f32 v[236:237], v[236:237], v[174:175]
	v_cvt_pk_bf16_f32 v230, v230, v231
	v_cvt_pk_bf16_f32 v231, v232, v233
	v_cvt_pk_bf16_f32 v232, v234, v235
	v_cvt_pk_bf16_f32 v233, v236, v237
	global_store_dwordx4 v185, v[230:233], s[98:99] offset:0
	s_add_u32 s98, s98, 0x10000
	s_addc_u32 s99, s99, 0
	s_waitcnt vmcnt(8) lgkmcnt(0)
	v_pk_fma_f32 v[240:241], v[240:241], s[24:25], v[176:177] op_sel_hi:[1,0,1]
	v_pk_fma_f32 v[242:243], v[242:243], s[24:25], v[178:179] op_sel_hi:[1,0,1]
	v_pk_fma_f32 v[244:245], v[244:245], s[24:25], v[180:181] op_sel_hi:[1,0,1]
	v_pk_fma_f32 v[246:247], v[246:247], s[24:25], v[182:183] op_sel_hi:[1,0,1]
	v_add_u32_e32 v186, 0x4200, v186
	ds_read_b128 v[176:179], v186
	ds_read_b128 v[180:183], v186 offset:16
	v_pk_add_f32 v[240:241], v[240:241], v[168:169]
	v_pk_add_f32 v[242:243], v[242:243], v[170:171]
	v_pk_add_f32 v[244:245], v[244:245], v[172:173]
	v_pk_add_f32 v[246:247], v[246:247], v[174:175]
	v_cvt_pk_bf16_f32 v240, v240, v241
	v_cvt_pk_bf16_f32 v241, v242, v243
	v_cvt_pk_bf16_f32 v242, v244, v245
	v_cvt_pk_bf16_f32 v243, v246, v247
	global_store_dwordx4 v185, v[240:243], s[98:99] offset:0
	s_add_u32 s98, s98, 0x10000
	s_addc_u32 s99, s99, 0
	s_waitcnt vmcnt(7) lgkmcnt(0)
	v_pk_fma_f32 v[248:249], v[248:249], s[24:25], v[176:177] op_sel_hi:[1,0,1]
	v_pk_fma_f32 v[250:251], v[250:251], s[24:25], v[178:179] op_sel_hi:[1,0,1]
	v_pk_fma_f32 v[252:253], v[252:253], s[24:25], v[180:181] op_sel_hi:[1,0,1]
	v_pk_fma_f32 v[254:255], v[254:255], s[24:25], v[182:183] op_sel_hi:[1,0,1]
	v_pk_add_f32 v[248:249], v[248:249], v[168:169]
	v_pk_add_f32 v[250:251], v[250:251], v[170:171]
	v_pk_add_f32 v[252:253], v[252:253], v[172:173]
	v_pk_add_f32 v[254:255], v[254:255], v[174:175]
	v_cvt_pk_bf16_f32 v248, v248, v249
	v_cvt_pk_bf16_f32 v249, v250, v251
	v_cvt_pk_bf16_f32 v250, v252, v253
	v_cvt_pk_bf16_f32 v251, v254, v255
	global_store_dwordx4 v185, v[248:251], s[98:99] offset:0
	v_readfirstlane_b32 s0, v0
	s_and_b32 s1, s0, 0xffffff00
	s_cmpk_lg_i32 s1, 0x100
	s_barrier
	s_cbranch_scc1 .LBB0_298
	s_lshl_b32 s0, s0, 1
	s_and_b32 s1, s0, 0x80
	v_or_b32_e32 v140, s1, v148
	s_and_b32 s0, s0, 0x100
	v_mul_u32_u24_e32 v140, 0x210, v140
	v_add3_u32 v140, v143, s0, v140
	ds_write2_b32 v140, v126, v122 offset1:16
	ds_write2_b32 v140, v127, v123 offset0:132 offset1:148
	v_add_u32_e32 v122, 0x400, v140
	ds_write2_b32 v122, v128, v124 offset0:8 offset1:24
	ds_write2_b32 v122, v129, v125 offset0:140 offset1:156
	ds_write2_b32 v140, v118, v114 offset0:32 offset1:48
	ds_write2_b32 v140, v119, v115 offset0:164 offset1:180
	ds_write2_b32 v122, v120, v116 offset0:40 offset1:56
	ds_write2_b32 v122, v121, v117 offset0:172 offset1:188
	v_add_u32_e32 v114, 0x2000, v140
	ds_write2_b32 v114, v110, v106 offset0:64 offset1:80
	ds_write2_b32 v114, v111, v107 offset0:196 offset1:212
	v_add_u32_e32 v106, 0x2400, v140
	ds_write2_b32 v106, v112, v108 offset0:72 offset1:88
	ds_write2_b32 v106, v113, v109 offset0:204 offset1:220
	ds_write2_b32 v114, v102, v98 offset0:96 offset1:112
	ds_write2_b32 v114, v103, v99 offset0:228 offset1:244
	ds_write2_b32 v106, v104, v100 offset0:104 offset1:120
	ds_write2_b32 v106, v105, v101 offset0:236 offset1:252
	v_add_u32_e32 v98, 0x4000, v140
	ds_write2_b32 v98, v94, v90 offset0:128 offset1:144
	v_add_u32_e32 v90, 0x4400, v140
	ds_write2_b32 v90, v95, v91 offset0:4 offset1:20
	ds_write2_b32 v90, v96, v92 offset0:136 offset1:152
	v_add_u32_e32 v91, 0x4800, v140
	ds_write2_b32 v91, v97, v93 offset0:12 offset1:28
	ds_write2_b32 v98, v86, v82 offset0:160 offset1:176
	ds_write2_b32 v90, v87, v83 offset0:36 offset1:52
	ds_write2_b32 v90, v88, v84 offset0:168 offset1:184
	ds_write2_b32 v91, v89, v85 offset0:44 offset1:60
	v_add_u32_e32 v82, 0x6000, v140
	ds_write2_b32 v82, v78, v74 offset0:192 offset1:208
	v_add_u32_e32 v74, 0x6400, v140
	ds_write2_b32 v74, v79, v75 offset0:68 offset1:84
	ds_write2_b32 v74, v80, v76 offset0:200 offset1:216
	v_add_u32_e32 v75, 0x6800, v140
	ds_write2_b32 v75, v81, v77 offset0:76 offset1:92
	ds_write2_b32 v82, v66, v62 offset0:224 offset1:240
	ds_write2_b32 v74, v67, v63 offset0:100 offset1:116
	ds_write2_b32 v74, v68, v64 offset0:232 offset1:248
; DI unsigned pack2(float a, float b) { const f32x2 v = {a, b}; const bf16x2_t r = __builtin_convertvector(v, bf16x2_t); return __builtin_bit_cast(unsigned, r); }
; template <int HF>
; DI void stage_acc_big(const f32x4 (&acc)[8][4], char* smem, const int g, const int r16) {
;   const int w = __builtin_amdgcn_readfirstlane(threadIdx.x >> 6), wm = w & 1, wn = w >> 1;
;   if ((wn >> 1) != HF) return;
;   float* ct = (float*)smem;
; #pragma unroll
;   for (int mi = 0; mi < 8; ++mi)
; #pragma unroll
;     for (int ni = 0; ni < 4; ++ni)
; #pragma unroll
;       for (int j = 0; j < 4; ++j) ct[(128 * wm + 16 * mi + 4 * g + j) * CT_PITCH + 64 * (wn & 1) + 16 * ni + r16] = acc[mi][ni][j];
; }
; DI void outproj_epilogue(const Params& p, const char* smem, const int m0, const int n0) {
;   u16* rbuf = (u16*)(p.ws + WS_PU);
;   const float* ct = (const float*)smem;
; #pragma unroll 4
;   for (int i = 0; i < 16; ++i) {
;     const int c = threadIdx.x + NT * i, row = c >> 5, ch = c & 31;
;     const float4 y = *(const float4*)(ct + row * CT_PITCH + 4 * ch);
;     const size_t o = (size_t)(m0 + row) * 1024 + n0 + 4 * ch;
;     const float4 xv = *(const float4*)(p.x + o), bv = *(const float4*)(p.b_out + n0 + 4 * ch);
;     uint2 r; r.x = pack2(ALPHA * xv.x + y.x + bv.x, ALPHA * xv.y + y.y + bv.y); r.y = pack2(ALPHA * xv.z + y.z + bv.z, ALPHA * xv.w + y.w + bv.w);
;     *(uint2*)(rbuf + o) = r;
;   }
	ds_write2_b32 v75, v69, v65 offset0:108 offset1:124
	v_add_u32_e32 v62, 0x8400, v140
	ds_write2_b32 v62, v58, v54 offset1:16
	ds_write2_b32 v62, v59, v55 offset0:132 offset1:148
	v_add_u32_e32 v54, 0x8800, v140
	ds_write2_b32 v54, v60, v56 offset0:8 offset1:24
	ds_write2_b32 v54, v61, v57 offset0:140 offset1:156
	ds_write2_b32 v62, v50, v46 offset0:32 offset1:48
	ds_write2_b32 v62, v51, v47 offset0:164 offset1:180
	ds_write2_b32 v54, v52, v48 offset0:40 offset1:56
	ds_write2_b32 v54, v53, v49 offset0:172 offset1:188
	v_add_u32_e32 v46, 0xa400, v140
	ds_write2_b32 v46, v42, v38 offset0:64 offset1:80
	ds_write2_b32 v46, v43, v39 offset0:196 offset1:212
	v_add_u32_e32 v38, 0xa800, v140
	ds_write2_b32 v38, v44, v40 offset0:72 offset1:88
	ds_write2_b32 v38, v45, v41 offset0:204 offset1:220
	ds_write2_b32 v46, v34, v30 offset0:96 offset1:112
	ds_write2_b32 v46, v35, v31 offset0:228 offset1:244
	ds_write2_b32 v38, v36, v32 offset0:104 offset1:120
	ds_write2_b32 v38, v37, v33 offset0:236 offset1:252
	v_add_u32_e32 v30, 0xc400, v140
	ds_write2_b32 v30, v26, v22 offset0:128 offset1:144
	v_add_u32_e32 v22, 0xc800, v140
	ds_write2_b32 v22, v27, v23 offset0:4 offset1:20
	ds_write2_b32 v22, v28, v24 offset0:136 offset1:152
	v_add_u32_e32 v23, 0xcc00, v140
	ds_write2_b32 v23, v29, v25 offset0:12 offset1:28
	ds_write2_b32 v30, v18, v14 offset0:160 offset1:176
	ds_write2_b32 v22, v19, v15 offset0:36 offset1:52
	ds_write2_b32 v22, v20, v16 offset0:168 offset1:184
	ds_write2_b32 v23, v21, v17 offset0:44 offset1:60
	v_add_u32_e32 v14, 0xe400, v140
	ds_write2_b32 v14, v10, v6 offset0:192 offset1:208
	v_add_u32_e32 v6, 0xe800, v140
	ds_write2_b32 v6, v11, v7 offset0:68 offset1:84
	ds_write2_b32 v6, v12, v8 offset0:200 offset1:216
	v_add_u32_e32 v7, 0xec00, v140
	ds_write2_b32 v7, v13, v9 offset0:76 offset1:92
	ds_write2_b32 v14, v2, v70 offset0:224 offset1:240
	ds_write2_b32 v6, v3, v71 offset0:100 offset1:116
	ds_write2_b32 v6, v4, v72 offset0:232 offset1:248
	ds_write2_b32 v7, v5, v73 offset0:108 offset1:124
.LBB0_298:
	s_or_b32 s0, s26, 0x80
	s_ashr_i32 s1, s0, 31
	v_mov_b32_e32 v3, s1
	v_or_b32_e32 v2, s0, v130
	v_lshl_add_u64 v[4:5], s[26:27], 0, v[130:131]
	s_mov_b32 s0, 0
	v_mov_b32_e32 v6, v154
	v_mov_b32_e32 v7, v152
	v_mov_b32_e32 v8, v150
	v_lshrrev_b32_e32 v187, 4, v0
	v_and_b32_e32 v186, 15, v0
	v_lshlrev_b32_e32 v186, 5, v186
	v_mul_u32_u24_e32 v187, 0x210, v187
	v_add_u32_e32 v186, v187, v186
	s_nop 1
	global_load_dwordx4 v[168:171], v164, s[100:101] offset:512
	global_load_dwordx4 v[172:175], v164, s[100:101] offset:528
	s_mov_b64 s[98:99], s[52:53]
	global_load_dwordx4 v[188:191], v184, s[98:99] offset:512
	global_load_dwordx4 v[192:195], v184, s[98:99] offset:528
	s_add_u32 s98, s98, 0x20000
	s_addc_u32 s99, s99, 0
	global_load_dwordx4 v[196:199], v184, s[98:99] offset:512
	global_load_dwordx4 v[202:205], v184, s[98:99] offset:528
	s_add_u32 s98, s98, 0x20000
	s_addc_u32 s99, s99, 0
	global_load_dwordx4 v[206:209], v184, s[98:99] offset:512
	global_load_dwordx4 v[210:213], v184, s[98:99] offset:528
	s_add_u32 s98, s98, 0x20000
	s_addc_u32 s99, s99, 0
	global_load_dwordx4 v[214:217], v184, s[98:99] offset:512
	global_load_dwordx4 v[218:221], v184, s[98:99] offset:528
	s_add_u32 s98, s98, 0x20000
	s_addc_u32 s99, s99, 0
	global_load_dwordx4 v[222:225], v184, s[98:99] offset:512
	global_load_dwordx4 v[226:229], v184, s[98:99] offset:528
	s_add_u32 s98, s98, 0x20000
	s_addc_u32 s99, s99, 0
	global_load_dwordx4 v[230:233], v184, s[98:99] offset:512
	global_load_dwordx4 v[234:237], v184, s[98:99] offset:528
	s_add_u32 s98, s98, 0x20000
	s_addc_u32 s99, s99, 0
	global_load_dwordx4 v[240:243], v184, s[98:99] offset:512
	global_load_dwordx4 v[244:247], v184, s[98:99] offset:528
	s_add_u32 s98, s98, 0x20000
	s_addc_u32 s99, s99, 0
	global_load_dwordx4 v[248:251], v184, s[98:99] offset:512
	global_load_dwordx4 v[252:255], v184, s[98:99] offset:528
	s_waitcnt lgkmcnt(0)
	s_barrier
	s_mov_b64 s[98:99], s[14:15]
	ds_read_b128 v[176:179], v186
	ds_read_b128 v[180:183], v186 offset:16
	s_waitcnt vmcnt(14) lgkmcnt(0)
	v_pk_fma_f32 v[188:189], v[188:189], s[24:25], v[176:177] op_sel_hi:[1,0,1]
	v_pk_fma_f32 v[190:191], v[190:191], s[24:25], v[178:179] op_sel_hi:[1,0,1]
	v_pk_fma_f32 v[192:193], v[192:193], s[24:25], v[180:181] op_sel_hi:[1,0,1]
	v_pk_fma_f32 v[194:195], v[194:195], s[24:25], v[182:183] op_sel_hi:[1,0,1]
	v_add_u32_e32 v186, 0x4200, v186
	ds_read_b128 v[176:179], v186
	ds_read_b128 v[180:183], v186 offset:16
	v_pk_add_f32 v[188:189], v[188:189], v[168:169]
	v_pk_add_f32 v[190:191], v[190:191], v[170:171]
	v_pk_add_f32 v[192:193], v[192:193], v[172:173]
	v_pk_add_f32 v[194:195], v[194:195], v[174:175]
	v_cvt_pk_bf16_f32 v188, v188, v189
	v_cvt_pk_bf16_f32 v189, v190, v191
	v_cvt_pk_bf16_f32 v190, v192, v193
	v_cvt_pk_bf16_f32 v191, v194, v195
	global_store_dwordx4 v185, v[188:191], s[98:99] offset:256
	s_add_u32 s98, s98, 0x10000
	s_addc_u32 s99, s99, 0
	s_waitcnt vmcnt(13) lgkmcnt(0)
	v_pk_fma_f32 v[196:197], v[196:197], s[24:25], v[176:177] op_sel_hi:[1,0,1]
	v_pk_fma_f32 v[198:199], v[198:199], s[24:25], v[178:179] op_sel_hi:[1,0,1]
	v_pk_fma_f32 v[202:203], v[202:203], s[24:25], v[180:181] op_sel_hi:[1,0,1]
	v_pk_fma_f32 v[204:205], v[204:205], s[24:25], v[182:183] op_sel_hi:[1,0,1]
	v_add_u32_e32 v186, 0x4200, v186
	ds_read_b128 v[176:179], v186
	ds_read_b128 v[180:183], v186 offset:16
	v_pk_add_f32 v[196:197], v[196:197], v[168:169]
	v_pk_add_f32 v[198:199], v[198:199], v[170:171]
	v_pk_add_f32 v[202:203], v[202:203], v[172:173]
	v_pk_add_f32 v[204:205], v[204:205], v[174:175]
	v_cvt_pk_bf16_f32 v196, v196, v197
	v_cvt_pk_bf16_f32 v197, v198, v199
	v_cvt_pk_bf16_f32 v198, v202, v203
	v_cvt_pk_bf16_f32 v199, v204, v205
	global_store_dwordx4 v185, v[196:199], s[98:99] offset:256
	s_add_u32 s98, s98, 0x10000
	s_addc_u32 s99, s99, 0
	s_waitcnt vmcnt(12) lgkmcnt(0)
; DI unsigned pack2(float a, float b) { const f32x2 v = {a, b}; const bf16x2_t r = __builtin_convertvector(v, bf16x2_t); return __builtin_bit_cast(unsigned, r); }
; DI void outproj_epilogue(const Params& p, const char* smem, const int m0, const int n0) {
;     ...
; #pragma unroll 4
;   for (int i = 0; i < 16; ++i) {
;     const int c = threadIdx.x + NT * i, row = c >> 5, ch = c & 31;
;     const float4 y = *(const float4*)(ct + row * CT_PITCH + 4 * ch);
;     const size_t o = (size_t)(m0 + row) * 1024 + n0 + 4 * ch;
;     const float4 xv = *(const float4*)(p.x + o), bv = *(const float4*)(p.b_out + n0 + 4 * ch);
;     uint2 r; r.x = pack2(ALPHA * xv.x + y.x + bv.x, ALPHA * xv.y + y.y + bv.y); r.y = pack2(ALPHA * xv.z + y.z + bv.z, ALPHA * xv.w + y.w + bv.w);
;     *(uint2*)(rbuf + o) = r;
;   }
	v_pk_fma_f32 v[206:207], v[206:207], s[24:25], v[176:177] op_sel_hi:[1,0,1]
	v_pk_fma_f32 v[208:209], v[208:209], s[24:25], v[178:179] op_sel_hi:[1,0,1]
	v_pk_fma_f32 v[210:211], v[210:211], s[24:25], v[180:181] op_sel_hi:[1,0,1]
	v_pk_fma_f32 v[212:213], v[212:213], s[24:25], v[182:183] op_sel_hi:[1,0,1]
	v_add_u32_e32 v186, 0x4200, v186
	ds_read_b128 v[176:179], v186
	ds_read_b128 v[180:183], v186 offset:16
	v_pk_add_f32 v[206:207], v[206:207], v[168:169]
	v_pk_add_f32 v[208:209], v[208:209], v[170:171]
	v_pk_add_f32 v[210:211], v[210:211], v[172:173]
	v_pk_add_f32 v[212:213], v[212:213], v[174:175]
	v_cvt_pk_bf16_f32 v206, v206, v207
	v_cvt_pk_bf16_f32 v207, v208, v209
	v_cvt_pk_bf16_f32 v208, v210, v211
	v_cvt_pk_bf16_f32 v209, v212, v213
	global_store_dwordx4 v185, v[206:209], s[98:99] offset:256
	s_add_u32 s98, s98, 0x10000
	s_addc_u32 s99, s99, 0
	s_waitcnt vmcnt(11) lgkmcnt(0)
	v_pk_fma_f32 v[214:215], v[214:215], s[24:25], v[176:177] op_sel_hi:[1,0,1]
	v_pk_fma_f32 v[216:217], v[216:217], s[24:25], v[178:179] op_sel_hi:[1,0,1]
	v_pk_fma_f32 v[218:219], v[218:219], s[24:25], v[180:181] op_sel_hi:[1,0,1]
	v_pk_fma_f32 v[220:221], v[220:221], s[24:25], v[182:183] op_sel_hi:[1,0,1]
	v_add_u32_e32 v186, 0x4200, v186
	ds_read_b128 v[176:179], v186
	ds_read_b128 v[180:183], v186 offset:16
	v_pk_add_f32 v[214:215], v[214:215], v[168:169]
	v_pk_add_f32 v[216:217], v[216:217], v[170:171]
	v_pk_add_f32 v[218:219], v[218:219], v[172:173]
	v_pk_add_f32 v[220:221], v[220:221], v[174:175]
	v_cvt_pk_bf16_f32 v214, v214, v215
	v_cvt_pk_bf16_f32 v215, v216, v217
	v_cvt_pk_bf16_f32 v216, v218, v219
	v_cvt_pk_bf16_f32 v217, v220, v221
	global_store_dwordx4 v185, v[214:217], s[98:99] offset:256
	s_add_u32 s98, s98, 0x10000
	s_addc_u32 s99, s99, 0
	s_waitcnt vmcnt(10) lgkmcnt(0)
	v_pk_fma_f32 v[222:223], v[222:223], s[24:25], v[176:177] op_sel_hi:[1,0,1]
	v_pk_fma_f32 v[224:225], v[224:225], s[24:25], v[178:179] op_sel_hi:[1,0,1]
	v_pk_fma_f32 v[226:227], v[226:227], s[24:25], v[180:181] op_sel_hi:[1,0,1]
	v_pk_fma_f32 v[228:229], v[228:229], s[24:25], v[182:183] op_sel_hi:[1,0,1]
	v_add_u32_e32 v186, 0x4200, v186
	ds_read_b128 v[176:179], v186
	ds_read_b128 v[180:183], v186 offset:16
	v_pk_add_f32 v[222:223], v[222:223], v[168:169]
	v_pk_add_f32 v[224:225], v[224:225], v[170:171]
	v_pk_add_f32 v[226:227], v[226:227], v[172:173]
	v_pk_add_f32 v[228:229], v[228:229], v[174:175]
	v_cvt_pk_bf16_f32 v222, v222, v223
	v_cvt_pk_bf16_f32 v223, v224, v225
	v_cvt_pk_bf16_f32 v224, v226, v227
	v_cvt_pk_bf16_f32 v225, v228, v229
	global_store_dwordx4 v185, v[222:225], s[98:99] offset:256
	s_add_u32 s98, s98, 0x10000
	s_addc_u32 s99, s99, 0
	s_waitcnt vmcnt(9) lgkmcnt(0)
	v_pk_fma_f32 v[230:231], v[230:231], s[24:25], v[176:177] op_sel_hi:[1,0,1]
	v_pk_fma_f32 v[232:233], v[232:233], s[24:25], v[178:179] op_sel_hi:[1,0,1]
	v_pk_fma_f32 v[234:235], v[234:235], s[24:25], v[180:181] op_sel_hi:[1,0,1]
	v_pk_fma_f32 v[236:237], v[236:237], s[24:25], v[182:183] op_sel_hi:[1,0,1]
	v_add_u32_e32 v186, 0x4200, v186
	ds_read_b128 v[176:179], v186
	ds_read_b128 v[180:183], v186 offset:16
	v_pk_add_f32 v[230:231], v[230:231], v[168:169]
	v_pk_add_f32 v[232:233], v[232:233], v[170:171]
	v_pk_add_f32 v[234:235], v[234:235], v[172:173]
	v_pk_add_f32 v[236:237], v[236:237], v[174:175]
	v_cvt_pk_bf16_f32 v230, v230, v231
	v_cvt_pk_bf16_f32 v231, v232, v233
	v_cvt_pk_bf16_f32 v232, v234, v235
	v_cvt_pk_bf16_f32 v233, v236, v237
	global_store_dwordx4 v185, v[230:233], s[98:99] offset:256
	s_add_u32 s98, s98, 0x10000
	s_addc_u32 s99, s99, 0
	s_waitcnt vmcnt(8) lgkmcnt(0)
	v_pk_fma_f32 v[240:241], v[240:241], s[24:25], v[176:177] op_sel_hi:[1,0,1]
	v_pk_fma_f32 v[242:243], v[242:243], s[24:25], v[178:179] op_sel_hi:[1,0,1]
	v_pk_fma_f32 v[244:245], v[244:245], s[24:25], v[180:181] op_sel_hi:[1,0,1]
	v_pk_fma_f32 v[246:247], v[246:247], s[24:25], v[182:183] op_sel_hi:[1,0,1]
	v_add_u32_e32 v186, 0x4200, v186
	ds_read_b128 v[176:179], v186
	ds_read_b128 v[180:183], v186 offset:16
	v_pk_add_f32 v[240:241], v[240:241], v[168:169]
	v_pk_add_f32 v[242:243], v[242:243], v[170:171]
	v_pk_add_f32 v[244:245], v[244:245], v[172:173]
	v_pk_add_f32 v[246:247], v[246:247], v[174:175]
	v_cvt_pk_bf16_f32 v240, v240, v241
	v_cvt_pk_bf16_f32 v241, v242, v243
	v_cvt_pk_bf16_f32 v242, v244, v245
	v_cvt_pk_bf16_f32 v243, v246, v247
	global_store_dwordx4 v185, v[240:243], s[98:99] offset:256
	s_add_u32 s98, s98, 0x10000
	s_addc_u32 s99, s99, 0
	s_waitcnt vmcnt(7) lgkmcnt(0)
	v_pk_fma_f32 v[248:249], v[248:249], s[24:25], v[176:177] op_sel_hi:[1,0,1]
	v_pk_fma_f32 v[250:251], v[250:251], s[24:25], v[178:179] op_sel_hi:[1,0,1]
	v_pk_fma_f32 v[252:253], v[252:253], s[24:25], v[180:181] op_sel_hi:[1,0,1]
	v_pk_fma_f32 v[254:255], v[254:255], s[24:25], v[182:183] op_sel_hi:[1,0,1]
	v_pk_add_f32 v[248:249], v[248:249], v[168:169]
	v_pk_add_f32 v[250:251], v[250:251], v[170:171]
	v_pk_add_f32 v[252:253], v[252:253], v[172:173]
	v_pk_add_f32 v[254:255], v[254:255], v[174:175]
	v_cvt_pk_bf16_f32 v248, v248, v249
	v_cvt_pk_bf16_f32 v249, v250, v251
	v_cvt_pk_bf16_f32 v250, v252, v253
	v_cvt_pk_bf16_f32 v251, v254, v255
	global_store_dwordx4 v185, v[248:251], s[98:99] offset:256
	s_add_i32 s31, s31, s3
	s_add_i32 s34, s34, 1
	s_cmpk_lt_i32 s31, 0x200
	s_barrier
	s_cbranch_scc1 .LBB0_286
	s_branch .LBB0_303
